# P8 K-loop LDS-DMA loads also converted to saddr form (no VALU address adds), on top of the P7 saddr version
# baseline (speedup 1.0000x reference)
; #define PG8_STAGE(bufoff, gbase, voff) do { _Pragma("unroll") for (int _i = 0; _i < 2; ++_i) \
;         __builtin_amdgcn_global_load_lds((const unsigned*)((const char*)(gbase) + (voff)[_i]), (LAS unsigned*)(lds + (bufoff) + ldsw + _i * 8192), 16, 0, 0); } while (0)
; #define PG8_LDA(dst, b, h) do { _Pragma("unroll") for (int m = 0; m < 4; ++m) _Pragma("unroll") for (int k = 0; k < 2; ++k) dst[m][k] = *(const LAS bf16x8*)(lds + PG8_SA(b, h) + aoff + m * 2048 + k * 1024); } while (0)
; #define PG8_LDB(dst, b, h) do { _Pragma("unroll") for (int n = 0; n < 2; ++n) _Pragma("unroll") for (int k = 0; k < 2; ++k) dst[n][k] = *(const LAS bf16x8*)(lds + PG8_SB(b, h) + boff + n * 2048 + k * 1024); } while (0)
; #define PG8_MMA(ai, bj, At, Bt) do { __builtin_amdgcn_s_setprio(1); _Pragma("unroll") for (int m = 0; m < 4; ++m) _Pragma("unroll") for (int n = 0; n < 2; ++n) _Pragma("unroll") for (int k = 0; k < 2; ++k) \
;         acc[ai][bj][m][n] = __builtin_amdgcn_mfma_f32_16x16x32_bf16(Bt[n][k], At[m][k], acc[ai][bj][m][n], 0, 0, 0); __builtin_amdgcn_s_setprio(0); } while (0)
; #define PG8_WAIT_V(n) asm volatile("s_waitcnt vmcnt(" #n ")" ::: "memory")
; #define PG8_WAIT_L(n) asm volatile("s_waitcnt lgkmcnt(" #n ")" ::: "memory")
; #define PG8_BAR __builtin_amdgcn_s_barrier()
; #define PG8_SCHED __builtin_amdgcn_sched_barrier(0)
; template <class Epi, class Sched>
; __device__ __forceinline__ void gemm_phase(LAS unsigned char* lds, const Gemm g, const Sched& S, const Epi& E) {
;     ...
;         for (int t = 0; t < nt; t += 2) {
;             const bool last = (t == nt - 2);
;             const char* a1 = cA + (size_t)(t + 1) * kstep;
;             const char* a2 = last ? nA : cA + (size_t)(t + 2) * kstep; const char* b2 = last ? nB : cB + (size_t)(t + 2) * kstep;
;             const char* a3 = a2 + kstep; const char* b3 = b2 + kstep;
;             PG8_LDB(B0, 0, 0); PG8_LDB(B1, 0, 1); PG8_SCHED; PG8_LDA(At, 0, 0); PG8_STAGE(PG8_SA(1, 1), a1 + hstepA, voffA);
;             PG8_WAIT_V(8); PG8_WAIT_L(0); PG8_BAR; PG8_MMA(0, 0, At, B0); PG8_MMA(0, 1, At, B1); PG8_BAR; PG8_SCHED;
;             PG8_LDA(At, 0, 1); PG8_STAGE(PG8_SB(0, 0), b2, voffB); PG8_STAGE(PG8_SB(0, 1), b2 + hstepB, voffB); PG8_STAGE(PG8_SA(0, 0), a2, voffA);
;             PG8_WAIT_V(8); PG8_WAIT_L(0); PG8_BAR; PG8_MMA(1, 0, At, B0); PG8_MMA(1, 1, At, B1); PG8_BAR; PG8_SCHED;
.Ledge_p8:
.LBB0_917:
	ds_read_b128 v[128:131], v208
	ds_read_b128 v[132:135], v208 offset:1024
	ds_read_b128 v[136:139], v208 offset:2048
	ds_read_b128 v[140:143], v208 offset:3072
	ds_read_b128 v[144:147], v209
	ds_read_b128 v[148:151], v209 offset:1024
	ds_read_b128 v[172:175], v209 offset:2048
	ds_read_b128 v[176:179], v209 offset:3072
	s_add_i32 s55, s47, 2
	s_add_u32 s57, s8, 0xffe00800
	s_addc_u32 s59, s9, -1
	s_cmp_eq_u32 s35, s47
	s_cselect_b32 s71, s2, s59
	s_cselect_b32 s70, s5, s57
	s_cselect_b32 s67, s19, s46
	s_cselect_b32 s66, s34, s41
	s_add_i32 m0, s17, 0xc000
	ds_read_b128 v[180:183], v210
	ds_read_b128 v[184:187], v210 offset:1024
	ds_read_b128 v[188:191], v210 offset:2048
	ds_read_b128 v[192:195], v210 offset:3072
	ds_read_b128 v[196:199], v210 offset:4096
	ds_read_b128 v[200:203], v210 offset:5120
	ds_read_b128 v[204:207], v210 offset:6144
	ds_read_b128 v[212:215], v210 offset:7168
	global_load_lds_dwordx4 v168, s[8:9]
	s_add_i32 m0, s17, 0xe000
	s_nop 0
	global_load_lds_dwordx4 v170, s[8:9]
	s_waitcnt vmcnt(8)
	s_waitcnt lgkmcnt(0)
	s_barrier
	s_setprio 1
	s_waitcnt lgkmcnt(0)
	v_mfma_f32_16x16x32_bf16 v[124:127], v[128:131], v[180:183], v[124:127]
	v_mfma_f32_16x16x32_bf16 v[120:123], v[136:139], v[180:183], v[120:123]
	v_mfma_f32_16x16x32_bf16 v[116:119], v[128:131], v[188:191], v[116:119]
	v_mfma_f32_16x16x32_bf16 v[112:115], v[136:139], v[188:191], v[112:115]
	v_mfma_f32_16x16x32_bf16 v[104:107], v[128:131], v[196:199], v[104:107]
	v_mfma_f32_16x16x32_bf16 v[96:99], v[136:139], v[196:199], v[96:99]
	v_mfma_f32_16x16x32_bf16 v[88:91], v[128:131], v[204:207], v[88:91]
	v_mfma_f32_16x16x32_bf16 v[80:83], v[136:139], v[204:207], v[80:83]
	v_mfma_f32_16x16x32_bf16 v[124:127], v[132:135], v[184:187], v[124:127]
	v_mfma_f32_16x16x32_bf16 v[120:123], v[140:143], v[184:187], v[120:123]
	v_mfma_f32_16x16x32_bf16 v[116:119], v[132:135], v[192:195], v[116:119]
	v_mfma_f32_16x16x32_bf16 v[112:115], v[140:143], v[192:195], v[112:115]
	v_mfma_f32_16x16x32_bf16 v[104:107], v[132:135], v[200:203], v[104:107]
	v_mfma_f32_16x16x32_bf16 v[96:99], v[140:143], v[200:203], v[96:99]
	v_mfma_f32_16x16x32_bf16 v[88:91], v[132:135], v[212:215], v[88:91]
	v_mfma_f32_16x16x32_bf16 v[80:83], v[140:143], v[212:215], v[80:83]
	s_setprio 0
	s_setprio 1
	v_mfma_f32_16x16x32_bf16 v[108:111], v[144:147], v[180:183], v[108:111]
	v_mfma_f32_16x16x32_bf16 v[100:103], v[172:175], v[180:183], v[100:103]
	v_mfma_f32_16x16x32_bf16 v[92:95], v[144:147], v[188:191], v[92:95]
	v_mfma_f32_16x16x32_bf16 v[84:87], v[172:175], v[188:191], v[84:87]
	v_mfma_f32_16x16x32_bf16 v[76:79], v[144:147], v[196:199], v[76:79]
	v_mfma_f32_16x16x32_bf16 v[72:75], v[172:175], v[196:199], v[72:75]
	v_mfma_f32_16x16x32_bf16 v[68:71], v[144:147], v[204:207], v[68:71]
	v_mfma_f32_16x16x32_bf16 v[64:67], v[172:175], v[204:207], v[64:67]
	v_mfma_f32_16x16x32_bf16 v[108:111], v[148:151], v[184:187], v[108:111]
	v_mfma_f32_16x16x32_bf16 v[100:103], v[176:179], v[184:187], v[100:103]
	v_mfma_f32_16x16x32_bf16 v[92:95], v[148:151], v[192:195], v[92:95]
	v_mfma_f32_16x16x32_bf16 v[84:87], v[176:179], v[192:195], v[84:87]
	v_mfma_f32_16x16x32_bf16 v[76:79], v[148:151], v[200:203], v[76:79]
	v_mfma_f32_16x16x32_bf16 v[72:75], v[176:179], v[200:203], v[72:75]
	v_mfma_f32_16x16x32_bf16 v[68:71], v[148:151], v[212:215], v[68:71]
	v_mfma_f32_16x16x32_bf16 v[64:67], v[176:179], v[212:215], v[64:67]
	s_setprio 0
	s_barrier
	s_add_i32 s47, s81, s39
	s_mov_b32 m0, s47
	ds_read_b128 v[180:183], v210 offset:16384
	ds_read_b128 v[184:187], v210 offset:17408
	ds_read_b128 v[188:191], v210 offset:18432
	ds_read_b128 v[192:195], v210 offset:19456
	ds_read_b128 v[196:199], v210 offset:20480
	ds_read_b128 v[200:203], v210 offset:21504
	ds_read_b128 v[204:207], v210 offset:22528
	ds_read_b128 v[212:215], v210 offset:23552
	global_load_lds_dwordx4 v156, s[66:67]
	s_add_i32 m0, s47, 0x2000
	s_add_u32 s90, s66, 0x200000
	s_addc_u32 s91, s67, 0
	s_add_i32 s47, s82, s39
	global_load_lds_dwordx4 v160, s[66:67]
	s_mov_b32 m0, s47
	s_nop 0
	global_load_lds_dwordx4 v156, s[90:91]
	s_add_i32 m0, s47, 0x2000
	s_nop 0
	global_load_lds_dwordx4 v160, s[90:91]
	s_mov_b32 m0, s17
	s_nop 0
	global_load_lds_dwordx4 v154, s[70:71]
	s_mov_b32 m0, s72
	s_nop 0
	global_load_lds_dwordx4 v158, s[70:71]
	s_waitcnt vmcnt(8)
	s_waitcnt lgkmcnt(0)
	s_barrier
	s_setprio 1
	s_waitcnt lgkmcnt(0)
	v_mfma_f32_16x16x32_bf16 v[60:63], v[128:131], v[180:183], v[60:63]
	v_mfma_f32_16x16x32_bf16 v[56:59], v[136:139], v[180:183], v[56:59]
	v_mfma_f32_16x16x32_bf16 v[52:55], v[128:131], v[188:191], v[52:55]
	v_mfma_f32_16x16x32_bf16 v[48:51], v[136:139], v[188:191], v[48:51]
	v_mfma_f32_16x16x32_bf16 v[40:43], v[128:131], v[196:199], v[40:43]
	v_mfma_f32_16x16x32_bf16 v[32:35], v[136:139], v[196:199], v[32:35]
	v_mfma_f32_16x16x32_bf16 v[24:27], v[128:131], v[204:207], v[24:27]
	v_mfma_f32_16x16x32_bf16 v[16:19], v[136:139], v[204:207], v[16:19]
	v_mfma_f32_16x16x32_bf16 v[60:63], v[132:135], v[184:187], v[60:63]
	v_mfma_f32_16x16x32_bf16 v[56:59], v[140:143], v[184:187], v[56:59]
	v_mfma_f32_16x16x32_bf16 v[52:55], v[132:135], v[192:195], v[52:55]
	v_mfma_f32_16x16x32_bf16 v[48:51], v[140:143], v[192:195], v[48:51]
	v_mfma_f32_16x16x32_bf16 v[40:43], v[132:135], v[200:203], v[40:43]
	v_mfma_f32_16x16x32_bf16 v[32:35], v[140:143], v[200:203], v[32:35]
	v_mfma_f32_16x16x32_bf16 v[24:27], v[132:135], v[212:215], v[24:27]
	v_mfma_f32_16x16x32_bf16 v[16:19], v[140:143], v[212:215], v[16:19]
	s_setprio 0
	s_setprio 1
	v_mfma_f32_16x16x32_bf16 v[44:47], v[144:147], v[180:183], v[44:47]
	v_mfma_f32_16x16x32_bf16 v[36:39], v[172:175], v[180:183], v[36:39]
	v_mfma_f32_16x16x32_bf16 v[28:31], v[144:147], v[188:191], v[28:31]
	v_mfma_f32_16x16x32_bf16 v[20:23], v[172:175], v[188:191], v[20:23]
	v_mfma_f32_16x16x32_bf16 v[12:15], v[144:147], v[196:199], v[12:15]
	v_mfma_f32_16x16x32_bf16 v[8:11], v[172:175], v[196:199], v[8:11]
	v_mfma_f32_16x16x32_bf16 v[4:7], v[144:147], v[204:207], v[4:7]
	v_mfma_f32_16x16x32_bf16 v[0:3], v[172:175], v[204:207], v[0:3]
	v_mfma_f32_16x16x32_bf16 v[44:47], v[148:151], v[184:187], v[44:47]
	v_mfma_f32_16x16x32_bf16 v[36:39], v[176:179], v[184:187], v[36:39]
	v_mfma_f32_16x16x32_bf16 v[28:31], v[148:151], v[192:195], v[28:31]
	v_mfma_f32_16x16x32_bf16 v[20:23], v[176:179], v[192:195], v[20:23]
	v_mfma_f32_16x16x32_bf16 v[12:15], v[148:151], v[200:203], v[12:15]
	v_mfma_f32_16x16x32_bf16 v[8:11], v[176:179], v[200:203], v[8:11]
	v_mfma_f32_16x16x32_bf16 v[4:7], v[148:151], v[212:215], v[4:7]
	v_mfma_f32_16x16x32_bf16 v[0:3], v[176:179], v[212:215], v[0:3]
	s_setprio 0
	s_barrier
; #define PG8_STAGE(bufoff, gbase, voff) do { _Pragma("unroll") for (int _i = 0; _i < 2; ++_i) \
;         __builtin_amdgcn_global_load_lds((const unsigned*)((const char*)(gbase) + (voff)[_i]), (LAS unsigned*)(lds + (bufoff) + ldsw + _i * 8192), 16, 0, 0); } while (0)
; #define PG8_LDA(dst, b, h) do { _Pragma("unroll") for (int m = 0; m < 4; ++m) _Pragma("unroll") for (int k = 0; k < 2; ++k) dst[m][k] = *(const LAS bf16x8*)(lds + PG8_SA(b, h) + aoff + m * 2048 + k * 1024); } while (0)
; #define PG8_LDB(dst, b, h) do { _Pragma("unroll") for (int n = 0; n < 2; ++n) _Pragma("unroll") for (int k = 0; k < 2; ++k) dst[n][k] = *(const LAS bf16x8*)(lds + PG8_SB(b, h) + boff + n * 2048 + k * 1024); } while (0)
; #define PG8_MMA(ai, bj, At, Bt) do { __builtin_amdgcn_s_setprio(1); _Pragma("unroll") for (int m = 0; m < 4; ++m) _Pragma("unroll") for (int n = 0; n < 2; ++n) _Pragma("unroll") for (int k = 0; k < 2; ++k) \
;         acc[ai][bj][m][n] = __builtin_amdgcn_mfma_f32_16x16x32_bf16(Bt[n][k], At[m][k], acc[ai][bj][m][n], 0, 0, 0); __builtin_amdgcn_s_setprio(0); } while (0)
; #define PG8_WAIT_V(n) asm volatile("s_waitcnt vmcnt(" #n ")" ::: "memory")
; #define PG8_WAIT_L(n) asm volatile("s_waitcnt lgkmcnt(" #n ")" ::: "memory")
; #define PG8_BAR __builtin_amdgcn_s_barrier()
; #define PG8_SCHED __builtin_amdgcn_sched_barrier(0)
; template <class Epi, class Sched>
; __device__ __forceinline__ void gemm_phase(LAS unsigned char* lds, const Gemm g, const Sched& S, const Epi& E) {
;     ...
;             PG8_LDB(B0, 1, 0); PG8_LDB(B1, 1, 1); PG8_SCHED; PG8_LDA(At, 1, 0); PG8_STAGE(PG8_SA(0, 1), a2 + hstepA, voffA);
;             PG8_WAIT_V(8); PG8_WAIT_L(0); PG8_BAR; PG8_MMA(0, 0, At, B0); PG8_MMA(0, 1, At, B1); PG8_BAR; PG8_SCHED;
;             PG8_LDA(At, 1, 1); PG8_STAGE(PG8_SB(1, 0), b3, voffB); PG8_STAGE(PG8_SB(1, 1), b3 + hstepB, voffB); PG8_STAGE(PG8_SA(1, 0), a3, voffA);
;             PG8_WAIT_V(8); PG8_WAIT_L(0); PG8_BAR; PG8_MMA(1, 0, At, B0); PG8_MMA(1, 1, At, B1); PG8_BAR; PG8_SCHED;
;         }
;         if (wr == 0) PG8_BAR;
	s_add_i32 s47, 0, 0x18000
	s_add_i32 s57, 0, 0x1c000
	v_add_u32_e32 v140, s47, v153
	v_add_u32_e32 v176, s57, v153
	ds_read_b128 v[128:131], v140
	ds_read_b128 v[132:135], v140 offset:1024
	ds_read_b128 v[136:139], v140 offset:2048
	ds_read_b128 v[140:143], v140 offset:3072
	ds_read_b128 v[144:147], v176
	ds_read_b128 v[148:151], v176 offset:1024
	ds_read_b128 v[172:175], v176 offset:2048
	ds_read_b128 v[176:179], v176 offset:3072
	s_add_u32 s70, s70, 0x200000
	s_addc_u32 s71, s71, 0
	s_mov_b32 m0, s73
	ds_read_b128 v[180:183], v210 offset:32768
	ds_read_b128 v[184:187], v210 offset:33792
	ds_read_b128 v[188:191], v210 offset:34816
	ds_read_b128 v[192:195], v210 offset:35840
	ds_read_b128 v[196:199], v210 offset:36864
	ds_read_b128 v[200:203], v210 offset:37888
	ds_read_b128 v[204:207], v210 offset:38912
	ds_read_b128 v[212:215], v210 offset:39936
	global_load_lds_dwordx4 v154, s[70:71]
	s_mov_b32 m0, s76
	s_nop 0
	global_load_lds_dwordx4 v158, s[70:71]
	s_waitcnt vmcnt(8)
	s_waitcnt lgkmcnt(0)
	s_barrier
	s_setprio 1
	s_waitcnt lgkmcnt(0)
	v_mfma_f32_16x16x32_bf16 v[124:127], v[128:131], v[180:183], v[124:127]
	v_mfma_f32_16x16x32_bf16 v[120:123], v[136:139], v[180:183], v[120:123]
	v_mfma_f32_16x16x32_bf16 v[116:119], v[128:131], v[188:191], v[116:119]
	v_mfma_f32_16x16x32_bf16 v[112:115], v[136:139], v[188:191], v[112:115]
	v_mfma_f32_16x16x32_bf16 v[104:107], v[128:131], v[196:199], v[104:107]
	v_mfma_f32_16x16x32_bf16 v[96:99], v[136:139], v[196:199], v[96:99]
	v_mfma_f32_16x16x32_bf16 v[88:91], v[128:131], v[204:207], v[88:91]
	v_mfma_f32_16x16x32_bf16 v[80:83], v[136:139], v[204:207], v[80:83]
	v_mfma_f32_16x16x32_bf16 v[124:127], v[132:135], v[184:187], v[124:127]
	v_mfma_f32_16x16x32_bf16 v[120:123], v[140:143], v[184:187], v[120:123]
	v_mfma_f32_16x16x32_bf16 v[116:119], v[132:135], v[192:195], v[116:119]
	v_mfma_f32_16x16x32_bf16 v[112:115], v[140:143], v[192:195], v[112:115]
	v_mfma_f32_16x16x32_bf16 v[104:107], v[132:135], v[200:203], v[104:107]
	v_mfma_f32_16x16x32_bf16 v[96:99], v[140:143], v[200:203], v[96:99]
	v_mfma_f32_16x16x32_bf16 v[88:91], v[132:135], v[212:215], v[88:91]
	v_mfma_f32_16x16x32_bf16 v[80:83], v[140:143], v[212:215], v[80:83]
	s_setprio 0
	s_setprio 1
	v_mfma_f32_16x16x32_bf16 v[108:111], v[144:147], v[180:183], v[108:111]
	v_mfma_f32_16x16x32_bf16 v[100:103], v[172:175], v[180:183], v[100:103]
	v_mfma_f32_16x16x32_bf16 v[92:95], v[144:147], v[188:191], v[92:95]
	v_mfma_f32_16x16x32_bf16 v[84:87], v[172:175], v[188:191], v[84:87]
	v_mfma_f32_16x16x32_bf16 v[76:79], v[144:147], v[196:199], v[76:79]
	v_mfma_f32_16x16x32_bf16 v[72:75], v[172:175], v[196:199], v[72:75]
	v_mfma_f32_16x16x32_bf16 v[68:71], v[144:147], v[204:207], v[68:71]
	v_mfma_f32_16x16x32_bf16 v[64:67], v[172:175], v[204:207], v[64:67]
	v_mfma_f32_16x16x32_bf16 v[108:111], v[148:151], v[184:187], v[108:111]
	v_mfma_f32_16x16x32_bf16 v[100:103], v[176:179], v[184:187], v[100:103]
	v_mfma_f32_16x16x32_bf16 v[92:95], v[148:151], v[192:195], v[92:95]
	v_mfma_f32_16x16x32_bf16 v[84:87], v[176:179], v[192:195], v[84:87]
	v_mfma_f32_16x16x32_bf16 v[76:79], v[148:151], v[200:203], v[76:79]
	v_mfma_f32_16x16x32_bf16 v[72:75], v[176:179], v[200:203], v[72:75]
	v_mfma_f32_16x16x32_bf16 v[68:71], v[148:151], v[212:215], v[68:71]
	v_mfma_f32_16x16x32_bf16 v[64:67], v[176:179], v[212:215], v[64:67]
	s_setprio 0
	s_barrier
	s_add_i32 s47, s47, s39
	s_add_u32 s100, s66, 0x80
	s_addc_u32 s101, s67, 0
	s_mov_b32 m0, s47
	ds_read_b128 v[180:183], v210 offset:49152
	ds_read_b128 v[184:187], v210 offset:50176
	ds_read_b128 v[188:191], v210 offset:51200
	ds_read_b128 v[192:195], v210 offset:52224
	ds_read_b128 v[196:199], v210 offset:53248
	ds_read_b128 v[200:203], v210 offset:54272
	ds_read_b128 v[204:207], v210 offset:55296
	ds_read_b128 v[212:215], v210 offset:56320
	global_load_lds_dwordx4 v156, s[100:101]
	s_add_i32 m0, s47, 0x2000
	s_add_u32 s66, s66, 0x200080
	s_addc_u32 s67, s67, 0
	s_add_i32 s47, s57, s39
	global_load_lds_dwordx4 v160, s[100:101]
	s_mov_b32 m0, s47
	s_nop 0
	global_load_lds_dwordx4 v156, s[66:67]
	s_add_i32 m0, s47, 0x2000
	s_nop 0
	global_load_lds_dwordx4 v160, s[66:67]
	s_add_u32 s100, s70, 0xffe00800
	s_addc_u32 s101, s71, -1
	s_mov_b32 m0, s79
	s_nop 0
	global_load_lds_dwordx4 v154, s[100:101]
	s_mov_b32 m0, s80
	s_nop 0
	global_load_lds_dwordx4 v158, s[100:101]
	s_waitcnt vmcnt(8)
	s_waitcnt lgkmcnt(0)
	s_barrier
	s_setprio 1
	s_waitcnt lgkmcnt(0)
	v_mfma_f32_16x16x32_bf16 v[60:63], v[128:131], v[180:183], v[60:63]
	v_mfma_f32_16x16x32_bf16 v[56:59], v[136:139], v[180:183], v[56:59]
	v_mfma_f32_16x16x32_bf16 v[52:55], v[128:131], v[188:191], v[52:55]
	v_mfma_f32_16x16x32_bf16 v[48:51], v[136:139], v[188:191], v[48:51]
	v_mfma_f32_16x16x32_bf16 v[40:43], v[128:131], v[196:199], v[40:43]
	v_mfma_f32_16x16x32_bf16 v[32:35], v[136:139], v[196:199], v[32:35]
	v_mfma_f32_16x16x32_bf16 v[24:27], v[128:131], v[204:207], v[24:27]
	v_mfma_f32_16x16x32_bf16 v[16:19], v[136:139], v[204:207], v[16:19]
	v_mfma_f32_16x16x32_bf16 v[60:63], v[132:135], v[184:187], v[60:63]
	v_mfma_f32_16x16x32_bf16 v[56:59], v[140:143], v[184:187], v[56:59]
	v_mfma_f32_16x16x32_bf16 v[52:55], v[132:135], v[192:195], v[52:55]
	v_mfma_f32_16x16x32_bf16 v[48:51], v[140:143], v[192:195], v[48:51]
	v_mfma_f32_16x16x32_bf16 v[40:43], v[132:135], v[200:203], v[40:43]
	v_mfma_f32_16x16x32_bf16 v[32:35], v[140:143], v[200:203], v[32:35]
	v_mfma_f32_16x16x32_bf16 v[24:27], v[132:135], v[212:215], v[24:27]
	v_mfma_f32_16x16x32_bf16 v[16:19], v[140:143], v[212:215], v[16:19]
	s_setprio 0
	s_setprio 1
	v_mfma_f32_16x16x32_bf16 v[44:47], v[144:147], v[180:183], v[44:47]
	v_mfma_f32_16x16x32_bf16 v[36:39], v[172:175], v[180:183], v[36:39]
	v_mfma_f32_16x16x32_bf16 v[28:31], v[144:147], v[188:191], v[28:31]
	v_mfma_f32_16x16x32_bf16 v[20:23], v[172:175], v[188:191], v[20:23]
	v_mfma_f32_16x16x32_bf16 v[12:15], v[144:147], v[196:199], v[12:15]
	v_mfma_f32_16x16x32_bf16 v[8:11], v[172:175], v[196:199], v[8:11]
	v_mfma_f32_16x16x32_bf16 v[4:7], v[144:147], v[204:207], v[4:7]
	v_mfma_f32_16x16x32_bf16 v[0:3], v[172:175], v[204:207], v[0:3]
	v_mfma_f32_16x16x32_bf16 v[44:47], v[148:151], v[184:187], v[44:47]
	v_mfma_f32_16x16x32_bf16 v[36:39], v[176:179], v[184:187], v[36:39]
	v_mfma_f32_16x16x32_bf16 v[28:31], v[148:151], v[192:195], v[28:31]
	v_mfma_f32_16x16x32_bf16 v[20:23], v[176:179], v[192:195], v[20:23]
	v_mfma_f32_16x16x32_bf16 v[12:15], v[148:151], v[200:203], v[12:15]
	v_mfma_f32_16x16x32_bf16 v[8:11], v[176:179], v[200:203], v[8:11]
	v_mfma_f32_16x16x32_bf16 v[4:7], v[148:151], v[212:215], v[4:7]
	v_mfma_f32_16x16x32_bf16 v[0:3], v[176:179], v[212:215], v[0:3]
	s_setprio 0
	s_barrier
	s_add_u32 s8, s8, 0x1000
	s_addc_u32 s9, s9, 0
	s_add_u32 s41, s41, 0x100
	s_addc_u32 s46, s46, 0
	s_cmp_ge_i32 s55, s4
	s_mov_b32 s47, s55
	s_cbranch_scc0 .LBB0_917
	s_and_b64 vcc, exec, s[36:37]
	s_cbranch_vccz .LBB0_922
	s_barrier
	s_cmp_lt_i32 s12, 0
	s_mov_b64 s[8:9], -1
	s_cbranch_scc1 .LBB0_923
